# v6 + out-projection epilogue: one wait for the second half's 12 loads instead of a vmcnt ladder that also drained the write-through stores and f32 atomics
# baseline (speedup 1.0000x reference)
; __device__ __forceinline__ float dot4(f32x4 a) { return (a[0] * a[0] + a[1] * a[1]) + (a[2] * a[2] + a[3] * a[3]); }
; __device__ __forceinline__ void store16_wt(void* p, u32x4 v) { asm volatile("global_store_dwordx4 %0, %1, off sc1\n\ts_nop 1" :: "v"(p), "v"(v) : "memory"); }
; __device__ __forceinline__ u32x4 pack8(f32x4 a, f32x4 b) { u32x4 w; w.x = cvt_pk_bf16(a[0], a[1]); w.y = cvt_pk_bf16(a[2], a[3]); w.z = cvt_pk_bf16(b[0], b[1]); w.w = cvt_pk_bf16(b[2], b[3]); return w; }
;     __device__ __forceinline__ void operator()(const f32x4 (&acc)[2][2][4][2], const Unit& u, int wr, int wc, int fr, int fq) const {
;     ...
;             for (int m = 0; m < 4; ++m) {
;                 const int row = row0 + ai * HALF + m * 16;
;                 float ss = 0.f; const float r = rms[m];
; #pragma unroll
;                 for (int bj = 0; bj < 2; ++bj) { const int col = col0 + bj * HALF; const u32x4 w = xw[m][bj];
;                     const f32x4 a = (f32x4){__builtin_bit_cast(float, w.x << 16), __builtin_bit_cast(float, w.x & 0xffff0000u), __builtin_bit_cast(float, w.y << 16), __builtin_bit_cast(float, w.y & 0xffff0000u)} * r + acc[ai][bj][m][0],
;                                 b = (f32x4){__builtin_bit_cast(float, w.z << 16), __builtin_bit_cast(float, w.z & 0xffff0000u), __builtin_bit_cast(float, w.w << 16), __builtin_bit_cast(float, w.w & 0xffff0000u)} * r + acc[ai][bj][m][1];
;                     ss += dot4(a) + dot4(b);
;                     store16_wt(X1B + (size_t)row * 1024 + col, pack8(a, b)); }
;                 ss += __shfl_xor(ss, 16); ss += __shfl_xor(ss, 32);
;                 if (fq == 0) __hip_atomic_fetch_add(RSS + row, ss, __ATOMIC_RELAXED, __HIP_MEMORY_SCOPE_AGENT);
.LBB0_734:
	s_or_b64 exec, exec, s[24:25]
	s_waitcnt vmcnt(3)
	v_lshlrev_b32_e32 v50, 16, v86
	s_waitcnt lgkmcnt(0)
	v_and_b32_e32 v51, 0xffff0000, v86
	v_lshlrev_b32_e32 v52, 16, v87
	v_and_b32_e32 v53, 0xffff0000, v87
	v_pk_fma_f32 v[48:49], v[104:105], v[52:53], v[48:49] op_sel_hi:[0,1,1]
	v_pk_fma_f32 v[46:47], v[104:105], v[50:51], v[46:47] op_sel_hi:[0,1,1]
	v_lshlrev_b32_e32 v50, 16, v88
	v_and_b32_e32 v51, 0xffff0000, v88
	v_lshlrev_b32_e32 v52, 16, v89
	v_and_b32_e32 v53, 0xffff0000, v89
	v_pk_fma_f32 v[52:53], v[104:105], v[52:53], v[44:45] op_sel_hi:[0,1,1]
	v_pk_fma_f32 v[44:45], v[104:105], v[50:51], v[42:43] op_sel_hi:[0,1,1]
	v_mul_f32_e32 v42, v47, v47
	v_mul_f32_e32 v43, v49, v49
	v_fmac_f32_e32 v42, v46, v46
	v_fmac_f32_e32 v43, v48, v48
	v_add_f32_e32 v42, v42, v43
	v_mul_f32_e32 v43, v45, v45
	v_mul_f32_e32 v50, v53, v53
	v_fmac_f32_e32 v43, v44, v44
	v_fmac_f32_e32 v50, v52, v52
	v_add_f32_e32 v43, v43, v50
	v_add_f32_e32 v54, v42, v43
	v_lshl_add_u64 v[42:43], s[12:13], 0, v[106:107]
	v_lshl_add_u64 v[50:51], v[154:155], 1, v[42:43]
	v_cvt_pk_bf16_f32 v42, v46, v47
	v_cvt_pk_bf16_f32 v43, v48, v49
	v_cvt_pk_bf16_f32 v44, v44, v45
	v_cvt_pk_bf16_f32 v45, v52, v53
	global_store_dwordx4 v[50:51], v[42:45], off sc1
	s_nop 1
	v_lshlrev_b32_e32 v42, 16, v82
	v_and_b32_e32 v43, 0xffff0000, v82
	v_lshlrev_b32_e32 v44, 16, v83
	v_and_b32_e32 v45, 0xffff0000, v83
	v_pk_fma_f32 v[40:41], v[104:105], v[44:45], v[40:41] op_sel_hi:[0,1,1]
	v_pk_fma_f32 v[38:39], v[104:105], v[42:43], v[38:39] op_sel_hi:[0,1,1]
	v_lshlrev_b32_e32 v44, 16, v85
	v_and_b32_e32 v45, 0xffff0000, v85
	v_lshlrev_b32_e32 v42, 16, v84
	v_and_b32_e32 v43, 0xffff0000, v84
	v_pk_fma_f32 v[44:45], v[104:105], v[44:45], v[36:37] op_sel_hi:[0,1,1]
	v_mul_f32_e32 v36, v39, v39
	v_mul_f32_e32 v37, v41, v41
	v_pk_fma_f32 v[34:35], v[104:105], v[42:43], v[34:35] op_sel_hi:[0,1,1]
	v_fmac_f32_e32 v36, v38, v38
	v_fmac_f32_e32 v37, v40, v40
	v_add_f32_e32 v36, v36, v37
	v_mul_f32_e32 v37, v35, v35
	v_mul_f32_e32 v42, v45, v45
	v_fmac_f32_e32 v37, v34, v34
	v_fmac_f32_e32 v42, v44, v44
	v_add_f32_e32 v37, v37, v42
	v_add_f32_e32 v36, v36, v37
	v_add_f32_e32 v46, v54, v36
	ds_bpermute_b32 v47, v114, v46
	v_cvt_pk_bf16_f32 v36, v38, v39
	v_cvt_pk_bf16_f32 v38, v34, v35
	v_lshl_add_u64 v[42:43], v[50:51], 0, s[8:9]
	v_cvt_pk_bf16_f32 v37, v40, v41
	s_waitcnt lgkmcnt(0)
	v_add_f32_e32 v34, v46, v47
	ds_bpermute_b32 v35, v115, v34
	v_cvt_pk_bf16_f32 v39, v44, v45
	global_store_dwordx4 v[42:43], v[36:39], off sc1
	s_nop 1
	s_and_saveexec_b64 s[8:9], vcc
	s_cbranch_execz .LBB0_736
	v_lshl_add_u64 v[36:37], v[102:103], 2, s[10:11]
	s_waitcnt lgkmcnt(0)
	v_add_f32_e32 v34, v34, v35
	global_atomic_add_f32 v[36:37], v34, off
; __device__ __forceinline__ float dot4(f32x4 a) { return (a[0] * a[0] + a[1] * a[1]) + (a[2] * a[2] + a[3] * a[3]); }
; __device__ __forceinline__ void store16_wt(void* p, u32x4 v) { asm volatile("global_store_dwordx4 %0, %1, off sc1\n\ts_nop 1" :: "v"(p), "v"(v) : "memory"); }
; __device__ __forceinline__ u32x4 pack8(f32x4 a, f32x4 b) { u32x4 w; w.x = cvt_pk_bf16(a[0], a[1]); w.y = cvt_pk_bf16(a[2], a[3]); w.z = cvt_pk_bf16(b[0], b[1]); w.w = cvt_pk_bf16(b[2], b[3]); return w; }
;     __device__ __forceinline__ void operator()(const f32x4 (&acc)[2][2][4][2], const Unit& u, int wr, int wc, int fr, int fq) const {
;     ...
;             for (int m = 0; m < 4; ++m) {
;                 const int row = row0 + ai * HALF + m * 16;
;                 float ss = 0.f; const float r = rms[m];
; #pragma unroll
;                 for (int bj = 0; bj < 2; ++bj) { const int col = col0 + bj * HALF; const u32x4 w = xw[m][bj];
;                     const f32x4 a = (f32x4){__builtin_bit_cast(float, w.x << 16), __builtin_bit_cast(float, w.x & 0xffff0000u), __builtin_bit_cast(float, w.y << 16), __builtin_bit_cast(float, w.y & 0xffff0000u)} * r + acc[ai][bj][m][0],
;                                 b = (f32x4){__builtin_bit_cast(float, w.z << 16), __builtin_bit_cast(float, w.z & 0xffff0000u), __builtin_bit_cast(float, w.w << 16), __builtin_bit_cast(float, w.w & 0xffff0000u)} * r + acc[ai][bj][m][1];
;                     ss += dot4(a) + dot4(b);
;                     store16_wt(X1B + (size_t)row * 1024 + col, pack8(a, b)); }
;                 ss += __shfl_xor(ss, 16); ss += __shfl_xor(ss, 32);
;                 if (fq == 0) __hip_atomic_fetch_add(RSS + row, ss, __ATOMIC_RELAXED, __HIP_MEMORY_SCOPE_AGENT);
.LBB0_736:
	s_or_b64 exec, exec, s[8:9]
	v_lshlrev_b32_e32 v34, 16, v78
	s_waitcnt lgkmcnt(0)
	v_and_b32_e32 v35, 0xffff0000, v78
	v_lshlrev_b32_e32 v36, 16, v79
	v_and_b32_e32 v37, 0xffff0000, v79
	v_pk_fma_f32 v[32:33], v[98:99], v[36:37], v[32:33] op_sel_hi:[0,1,1]
	v_pk_fma_f32 v[30:31], v[98:99], v[34:35], v[30:31] op_sel_hi:[0,1,1]
	v_lshlrev_b32_e32 v34, 16, v80
	v_and_b32_e32 v35, 0xffff0000, v80
	v_lshlrev_b32_e32 v36, 16, v81
	v_and_b32_e32 v37, 0xffff0000, v81
	v_pk_fma_f32 v[36:37], v[98:99], v[36:37], v[28:29] op_sel_hi:[0,1,1]
	v_pk_fma_f32 v[28:29], v[98:99], v[34:35], v[26:27] op_sel_hi:[0,1,1]
	v_mul_f32_e32 v26, v31, v31
	v_mul_f32_e32 v27, v33, v33
	v_fmac_f32_e32 v26, v30, v30
	v_fmac_f32_e32 v27, v32, v32
	v_add_f32_e32 v26, v26, v27
	v_mul_f32_e32 v27, v29, v29
	v_mul_f32_e32 v34, v37, v37
	v_fmac_f32_e32 v27, v28, v28
	v_fmac_f32_e32 v34, v36, v36
	v_add_f32_e32 v27, v27, v34
	v_add_f32_e32 v38, v26, v27
	v_lshl_add_u64 v[26:27], s[12:13], 0, v[100:101]
	v_lshl_add_u64 v[34:35], v[154:155], 1, v[26:27]
	v_cvt_pk_bf16_f32 v26, v30, v31
	v_cvt_pk_bf16_f32 v27, v32, v33
	v_cvt_pk_bf16_f32 v28, v28, v29
	v_cvt_pk_bf16_f32 v29, v36, v37
	global_store_dwordx4 v[34:35], v[26:29], off sc1
	s_nop 1
	v_lshlrev_b32_e32 v26, 16, v74
	v_and_b32_e32 v27, 0xffff0000, v74
	v_lshlrev_b32_e32 v28, 16, v75
	v_and_b32_e32 v29, 0xffff0000, v75
	v_pk_fma_f32 v[24:25], v[98:99], v[28:29], v[24:25] op_sel_hi:[0,1,1]
	v_pk_fma_f32 v[22:23], v[98:99], v[26:27], v[22:23] op_sel_hi:[0,1,1]
	v_lshlrev_b32_e32 v28, 16, v77
	v_and_b32_e32 v29, 0xffff0000, v77
	v_lshlrev_b32_e32 v26, 16, v76
	v_and_b32_e32 v27, 0xffff0000, v76
	v_pk_fma_f32 v[28:29], v[98:99], v[28:29], v[20:21] op_sel_hi:[0,1,1]
	v_mul_f32_e32 v20, v23, v23
	v_mul_f32_e32 v21, v25, v25
	v_pk_fma_f32 v[18:19], v[98:99], v[26:27], v[18:19] op_sel_hi:[0,1,1]
	v_fmac_f32_e32 v20, v22, v22
	v_fmac_f32_e32 v21, v24, v24
	v_add_f32_e32 v20, v20, v21
	v_mul_f32_e32 v21, v19, v19
	v_mul_f32_e32 v26, v29, v29
	v_fmac_f32_e32 v21, v18, v18
	v_fmac_f32_e32 v26, v28, v28
	v_add_f32_e32 v21, v21, v26
	v_add_f32_e32 v20, v20, v21
	v_add_f32_e32 v30, v38, v20
	ds_bpermute_b32 v31, v114, v30
	v_cvt_pk_bf16_f32 v20, v22, v23
	v_cvt_pk_bf16_f32 v22, v18, v19
	s_mov_b64 s[8:9], 0x100
	v_lshl_add_u64 v[26:27], v[34:35], 0, s[8:9]
	s_waitcnt lgkmcnt(0)
	v_add_f32_e32 v18, v30, v31
	ds_bpermute_b32 v19, v115, v18
	v_cvt_pk_bf16_f32 v21, v24, v25
	v_cvt_pk_bf16_f32 v23, v28, v29
	global_store_dwordx4 v[26:27], v[20:23], off sc1
	s_nop 1
	s_and_saveexec_b64 s[24:25], vcc
	s_cbranch_execz .LBB0_738
	v_lshl_add_u64 v[20:21], v[96:97], 2, s[10:11]
	s_waitcnt lgkmcnt(0)
	v_add_f32_e32 v18, v18, v19
	global_atomic_add_f32 v[20:21], v18, off
.LBB0_738:
	s_or_b64 exec, exec, s[24:25]
	v_lshlrev_b32_e32 v18, 16, v70
	s_waitcnt lgkmcnt(0)
	v_and_b32_e32 v19, 0xffff0000, v70
	v_lshlrev_b32_e32 v20, 16, v71
	v_and_b32_e32 v21, 0xffff0000, v71
	v_pk_fma_f32 v[16:17], v[92:93], v[20:21], v[16:17] op_sel_hi:[0,1,1]
	v_pk_fma_f32 v[14:15], v[92:93], v[18:19], v[14:15] op_sel_hi:[0,1,1]
	v_lshlrev_b32_e32 v18, 16, v72
	v_and_b32_e32 v19, 0xffff0000, v72
	v_lshlrev_b32_e32 v20, 16, v73
	v_and_b32_e32 v21, 0xffff0000, v73
	v_pk_fma_f32 v[20:21], v[92:93], v[20:21], v[12:13] op_sel_hi:[0,1,1]
	v_pk_fma_f32 v[12:13], v[92:93], v[18:19], v[10:11] op_sel_hi:[0,1,1]
	v_mul_f32_e32 v10, v15, v15
	v_mul_f32_e32 v11, v17, v17
	v_fmac_f32_e32 v10, v14, v14
	v_fmac_f32_e32 v11, v16, v16
	v_add_f32_e32 v10, v10, v11
	v_mul_f32_e32 v11, v13, v13
	v_mul_f32_e32 v18, v21, v21
	v_fmac_f32_e32 v11, v12, v12
	v_fmac_f32_e32 v18, v20, v20
	v_add_f32_e32 v11, v11, v18
	v_add_f32_e32 v22, v10, v11
	v_lshl_add_u64 v[10:11], s[12:13], 0, v[94:95]
	v_lshl_add_u64 v[18:19], v[154:155], 1, v[10:11]
	v_cvt_pk_bf16_f32 v10, v14, v15
	v_cvt_pk_bf16_f32 v11, v16, v17
	v_cvt_pk_bf16_f32 v12, v12, v13
	v_cvt_pk_bf16_f32 v13, v20, v21
	global_store_dwordx4 v[18:19], v[10:13], off sc1
	s_nop 1
	v_lshlrev_b32_e32 v10, 16, v66
	v_and_b32_e32 v11, 0xffff0000, v66
	v_lshlrev_b32_e32 v12, 16, v67
	v_and_b32_e32 v13, 0xffff0000, v67
	v_pk_fma_f32 v[8:9], v[92:93], v[12:13], v[8:9] op_sel_hi:[0,1,1]
	v_pk_fma_f32 v[6:7], v[92:93], v[10:11], v[6:7] op_sel_hi:[0,1,1]
	v_lshlrev_b32_e32 v12, 16, v69
	v_and_b32_e32 v13, 0xffff0000, v69
	v_lshlrev_b32_e32 v10, 16, v68
	v_and_b32_e32 v11, 0xffff0000, v68
	v_pk_fma_f32 v[12:13], v[92:93], v[12:13], v[4:5] op_sel_hi:[0,1,1]
	v_mul_f32_e32 v4, v7, v7
	v_mul_f32_e32 v5, v9, v9
	v_pk_fma_f32 v[2:3], v[92:93], v[10:11], v[2:3] op_sel_hi:[0,1,1]
	v_fmac_f32_e32 v4, v6, v6
	v_fmac_f32_e32 v5, v8, v8
	v_add_f32_e32 v4, v4, v5
	v_mul_f32_e32 v5, v3, v3
	v_mul_f32_e32 v10, v13, v13
	v_fmac_f32_e32 v5, v2, v2
	v_fmac_f32_e32 v10, v12, v12
	v_add_f32_e32 v5, v5, v10
	v_add_f32_e32 v4, v4, v5
	v_add_f32_e32 v14, v22, v4
	ds_bpermute_b32 v15, v114, v14
	v_cvt_pk_bf16_f32 v4, v6, v7
	v_cvt_pk_bf16_f32 v6, v2, v3
	v_lshl_add_u64 v[10:11], v[18:19], 0, s[8:9]
	v_cvt_pk_bf16_f32 v5, v8, v9
	s_waitcnt lgkmcnt(0)
	v_add_f32_e32 v2, v14, v15
	ds_bpermute_b32 v3, v115, v2
	v_cvt_pk_bf16_f32 v7, v12, v13
	global_store_dwordx4 v[10:11], v[4:7], off sc1
	s_nop 1
	s_and_saveexec_b64 s[8:9], vcc
	s_cbranch_execz .LBB0_740
	v_lshl_add_u64 v[4:5], v[90:91], 2, s[10:11]
	s_waitcnt lgkmcnt(0)
	v_add_f32_e32 v2, v2, v3
	global_atomic_add_f32 v[4:5], v2, off

; __device__ __forceinline__ float dot4(f32x4 a) { return (a[0] * a[0] + a[1] * a[1]) + (a[2] * a[2] + a[3] * a[3]); }
; __device__ __forceinline__ void store16_wt(void* p, u32x4 v) { asm volatile("global_store_dwordx4 %0, %1, off sc1\n\ts_nop 1" :: "v"(p), "v"(v) : "memory"); }
; __device__ __forceinline__ u32x4 pack8(f32x4 a, f32x4 b) { u32x4 w; w.x = cvt_pk_bf16(a[0], a[1]); w.y = cvt_pk_bf16(a[2], a[3]); w.z = cvt_pk_bf16(b[0], b[1]); w.w = cvt_pk_bf16(b[2], b[3]); return w; }
;     __device__ __forceinline__ void operator()(const f32x4 (&acc)[2][2][4][2], const Unit& u, int wr, int wc, int fr, int fq) const {
;     ...
;             for (int m = 0; m < 4; ++m) {
;                 const int row = row0 + ai * HALF + m * 16;
;                 float ss = 0.f; const float r = rms[m];
; #pragma unroll
;                 for (int bj = 0; bj < 2; ++bj) { const int col = col0 + bj * HALF; const u32x4 w = xw[m][bj];
;                     const f32x4 a = (f32x4){__builtin_bit_cast(float, w.x << 16), __builtin_bit_cast(float, w.x & 0xffff0000u), __builtin_bit_cast(float, w.y << 16), __builtin_bit_cast(float, w.y & 0xffff0000u)} * r + acc[ai][bj][m][0],
;                                 b = (f32x4){__builtin_bit_cast(float, w.z << 16), __builtin_bit_cast(float, w.z & 0xffff0000u), __builtin_bit_cast(float, w.w << 16), __builtin_bit_cast(float, w.w & 0xffff0000u)} * r + acc[ai][bj][m][1];
;                     ss += dot4(a) + dot4(b);
;                     store16_wt(X1B + (size_t)row * 1024 + col, pack8(a, b)); }
;                 ss += __shfl_xor(ss, 16); ss += __shfl_xor(ss, 32);
;                 if (fq == 0) __hip_atomic_fetch_add(RSS + row, ss, __ATOMIC_RELAXED, __HIP_MEMORY_SCOPE_AGENT);
.LBB0_780:
	s_or_b64 exec, exec, s[14:15]
	s_waitcnt vmcnt(3)
	v_lshlrev_b32_e32 v50, 16, v86
	s_waitcnt lgkmcnt(0)
	v_and_b32_e32 v51, 0xffff0000, v86
	v_lshlrev_b32_e32 v52, 16, v87
	v_and_b32_e32 v53, 0xffff0000, v87
	v_pk_fma_f32 v[48:49], v[104:105], v[52:53], v[48:49] op_sel_hi:[0,1,1]
	v_pk_fma_f32 v[46:47], v[104:105], v[50:51], v[46:47] op_sel_hi:[0,1,1]
	v_lshlrev_b32_e32 v50, 16, v88
	v_and_b32_e32 v51, 0xffff0000, v88
	v_lshlrev_b32_e32 v52, 16, v89
	v_and_b32_e32 v53, 0xffff0000, v89
	v_pk_fma_f32 v[52:53], v[104:105], v[52:53], v[44:45] op_sel_hi:[0,1,1]
	v_pk_fma_f32 v[44:45], v[104:105], v[50:51], v[42:43] op_sel_hi:[0,1,1]
	v_mul_f32_e32 v42, v47, v47
	v_mul_f32_e32 v43, v49, v49
	v_fmac_f32_e32 v42, v46, v46
	v_fmac_f32_e32 v43, v48, v48
	v_add_f32_e32 v42, v42, v43
	v_mul_f32_e32 v43, v45, v45
	v_mul_f32_e32 v50, v53, v53
	v_fmac_f32_e32 v43, v44, v44
	v_fmac_f32_e32 v50, v52, v52
	v_add_f32_e32 v43, v43, v50
	v_add_f32_e32 v54, v42, v43
	v_lshl_add_u64 v[42:43], s[12:13], 0, v[106:107]
	v_lshl_add_u64 v[50:51], v[154:155], 1, v[42:43]
	v_cvt_pk_bf16_f32 v42, v46, v47
	v_cvt_pk_bf16_f32 v43, v48, v49
	v_cvt_pk_bf16_f32 v44, v44, v45
	v_cvt_pk_bf16_f32 v45, v52, v53
	global_store_dwordx4 v[50:51], v[42:45], off sc1
	s_nop 1
	v_lshlrev_b32_e32 v42, 16, v82
	v_and_b32_e32 v43, 0xffff0000, v82
	v_lshlrev_b32_e32 v44, 16, v83
	v_and_b32_e32 v45, 0xffff0000, v83
	v_pk_fma_f32 v[40:41], v[104:105], v[44:45], v[40:41] op_sel_hi:[0,1,1]
	v_pk_fma_f32 v[38:39], v[104:105], v[42:43], v[38:39] op_sel_hi:[0,1,1]
	v_lshlrev_b32_e32 v44, 16, v85
	v_and_b32_e32 v45, 0xffff0000, v85
	v_lshlrev_b32_e32 v42, 16, v84
	v_and_b32_e32 v43, 0xffff0000, v84
	v_pk_fma_f32 v[44:45], v[104:105], v[44:45], v[36:37] op_sel_hi:[0,1,1]
	v_mul_f32_e32 v36, v39, v39
	v_mul_f32_e32 v37, v41, v41
	v_pk_fma_f32 v[34:35], v[104:105], v[42:43], v[34:35] op_sel_hi:[0,1,1]
	v_fmac_f32_e32 v36, v38, v38
	v_fmac_f32_e32 v37, v40, v40
	v_add_f32_e32 v36, v36, v37
	v_mul_f32_e32 v37, v35, v35
	v_mul_f32_e32 v42, v45, v45
	v_fmac_f32_e32 v37, v34, v34
	v_fmac_f32_e32 v42, v44, v44
	v_add_f32_e32 v37, v37, v42
	v_add_f32_e32 v36, v36, v37
	v_add_f32_e32 v46, v54, v36
	ds_bpermute_b32 v47, v114, v46
	v_cvt_pk_bf16_f32 v36, v38, v39
	v_cvt_pk_bf16_f32 v38, v34, v35
	v_lshl_add_u64 v[42:43], v[50:51], 0, s[8:9]
	v_cvt_pk_bf16_f32 v37, v40, v41
	s_waitcnt lgkmcnt(0)
	v_add_f32_e32 v34, v46, v47
	ds_bpermute_b32 v35, v115, v34
	v_cvt_pk_bf16_f32 v39, v44, v45
	global_store_dwordx4 v[42:43], v[36:39], off sc1
	s_nop 1
	s_and_saveexec_b64 s[8:9], vcc
	s_cbranch_execz .LBB0_782
	v_lshl_add_u64 v[36:37], v[102:103], 2, s[10:11]
	s_waitcnt lgkmcnt(0)
	v_add_f32_e32 v34, v34, v35
	global_atomic_add_f32 v[36:37], v34, off
; __device__ __forceinline__ float dot4(f32x4 a) { return (a[0] * a[0] + a[1] * a[1]) + (a[2] * a[2] + a[3] * a[3]); }
; __device__ __forceinline__ void store16_wt(void* p, u32x4 v) { asm volatile("global_store_dwordx4 %0, %1, off sc1\n\ts_nop 1" :: "v"(p), "v"(v) : "memory"); }
; __device__ __forceinline__ u32x4 pack8(f32x4 a, f32x4 b) { u32x4 w; w.x = cvt_pk_bf16(a[0], a[1]); w.y = cvt_pk_bf16(a[2], a[3]); w.z = cvt_pk_bf16(b[0], b[1]); w.w = cvt_pk_bf16(b[2], b[3]); return w; }
;     __device__ __forceinline__ void operator()(const f32x4 (&acc)[2][2][4][2], const Unit& u, int wr, int wc, int fr, int fq) const {
;     ...
;             for (int m = 0; m < 4; ++m) {
;                 const int row = row0 + ai * HALF + m * 16;
;                 float ss = 0.f; const float r = rms[m];
; #pragma unroll
;                 for (int bj = 0; bj < 2; ++bj) { const int col = col0 + bj * HALF; const u32x4 w = xw[m][bj];
;                     const f32x4 a = (f32x4){__builtin_bit_cast(float, w.x << 16), __builtin_bit_cast(float, w.x & 0xffff0000u), __builtin_bit_cast(float, w.y << 16), __builtin_bit_cast(float, w.y & 0xffff0000u)} * r + acc[ai][bj][m][0],
;                                 b = (f32x4){__builtin_bit_cast(float, w.z << 16), __builtin_bit_cast(float, w.z & 0xffff0000u), __builtin_bit_cast(float, w.w << 16), __builtin_bit_cast(float, w.w & 0xffff0000u)} * r + acc[ai][bj][m][1];
;                     ss += dot4(a) + dot4(b);
;                     store16_wt(X1B + (size_t)row * 1024 + col, pack8(a, b)); }
;                 ss += __shfl_xor(ss, 16); ss += __shfl_xor(ss, 32);
;                 if (fq == 0) __hip_atomic_fetch_add(RSS + row, ss, __ATOMIC_RELAXED, __HIP_MEMORY_SCOPE_AGENT);
.LBB0_782:
	s_or_b64 exec, exec, s[8:9]
	v_lshlrev_b32_e32 v34, 16, v78
	s_waitcnt lgkmcnt(0)
	v_and_b32_e32 v35, 0xffff0000, v78
	v_lshlrev_b32_e32 v36, 16, v79
	v_and_b32_e32 v37, 0xffff0000, v79
	v_pk_fma_f32 v[32:33], v[98:99], v[36:37], v[32:33] op_sel_hi:[0,1,1]
	v_pk_fma_f32 v[30:31], v[98:99], v[34:35], v[30:31] op_sel_hi:[0,1,1]
	v_lshlrev_b32_e32 v34, 16, v80
	v_and_b32_e32 v35, 0xffff0000, v80
	v_lshlrev_b32_e32 v36, 16, v81
	v_and_b32_e32 v37, 0xffff0000, v81
	v_pk_fma_f32 v[36:37], v[98:99], v[36:37], v[28:29] op_sel_hi:[0,1,1]
	v_pk_fma_f32 v[28:29], v[98:99], v[34:35], v[26:27] op_sel_hi:[0,1,1]
	v_mul_f32_e32 v26, v31, v31
	v_mul_f32_e32 v27, v33, v33
	v_fmac_f32_e32 v26, v30, v30
	v_fmac_f32_e32 v27, v32, v32
	v_add_f32_e32 v26, v26, v27
	v_mul_f32_e32 v27, v29, v29
	v_mul_f32_e32 v34, v37, v37
	v_fmac_f32_e32 v27, v28, v28
	v_fmac_f32_e32 v34, v36, v36
	v_add_f32_e32 v27, v27, v34
	v_add_f32_e32 v38, v26, v27
	v_lshl_add_u64 v[26:27], s[12:13], 0, v[100:101]
	v_lshl_add_u64 v[34:35], v[154:155], 1, v[26:27]
	v_cvt_pk_bf16_f32 v26, v30, v31
	v_cvt_pk_bf16_f32 v27, v32, v33
	v_cvt_pk_bf16_f32 v28, v28, v29
	v_cvt_pk_bf16_f32 v29, v36, v37
	global_store_dwordx4 v[34:35], v[26:29], off sc1
	s_nop 1
	v_lshlrev_b32_e32 v26, 16, v74
	v_and_b32_e32 v27, 0xffff0000, v74
	v_lshlrev_b32_e32 v28, 16, v75
	v_and_b32_e32 v29, 0xffff0000, v75
	v_pk_fma_f32 v[24:25], v[98:99], v[28:29], v[24:25] op_sel_hi:[0,1,1]
	v_pk_fma_f32 v[22:23], v[98:99], v[26:27], v[22:23] op_sel_hi:[0,1,1]
	v_lshlrev_b32_e32 v28, 16, v77
	v_and_b32_e32 v29, 0xffff0000, v77
	v_lshlrev_b32_e32 v26, 16, v76
	v_and_b32_e32 v27, 0xffff0000, v76
	v_pk_fma_f32 v[28:29], v[98:99], v[28:29], v[20:21] op_sel_hi:[0,1,1]
	v_mul_f32_e32 v20, v23, v23
	v_mul_f32_e32 v21, v25, v25
	v_pk_fma_f32 v[18:19], v[98:99], v[26:27], v[18:19] op_sel_hi:[0,1,1]
	v_fmac_f32_e32 v20, v22, v22
	v_fmac_f32_e32 v21, v24, v24
	v_add_f32_e32 v20, v20, v21
	v_mul_f32_e32 v21, v19, v19
	v_mul_f32_e32 v26, v29, v29
	v_fmac_f32_e32 v21, v18, v18
	v_fmac_f32_e32 v26, v28, v28
	v_add_f32_e32 v21, v21, v26
	v_add_f32_e32 v20, v20, v21
	v_add_f32_e32 v30, v38, v20
	ds_bpermute_b32 v31, v114, v30
	v_cvt_pk_bf16_f32 v20, v22, v23
	v_cvt_pk_bf16_f32 v22, v18, v19
	s_mov_b64 s[8:9], 0x100
	v_lshl_add_u64 v[26:27], v[34:35], 0, s[8:9]
	s_waitcnt lgkmcnt(0)
	v_add_f32_e32 v18, v30, v31
	ds_bpermute_b32 v19, v115, v18
	v_cvt_pk_bf16_f32 v21, v24, v25
	v_cvt_pk_bf16_f32 v23, v28, v29
	global_store_dwordx4 v[26:27], v[20:23], off sc1
	s_nop 1
	s_and_saveexec_b64 s[14:15], vcc
	s_cbranch_execz .LBB0_784
	v_lshl_add_u64 v[20:21], v[96:97], 2, s[10:11]
	s_waitcnt lgkmcnt(0)
	v_add_f32_e32 v18, v18, v19
	global_atomic_add_f32 v[20:21], v18, off
.LBB0_784:
	s_or_b64 exec, exec, s[14:15]
	v_lshlrev_b32_e32 v18, 16, v70
	s_waitcnt lgkmcnt(0)
	v_and_b32_e32 v19, 0xffff0000, v70
	v_lshlrev_b32_e32 v20, 16, v71
	v_and_b32_e32 v21, 0xffff0000, v71
	v_pk_fma_f32 v[16:17], v[92:93], v[20:21], v[16:17] op_sel_hi:[0,1,1]
	v_pk_fma_f32 v[14:15], v[92:93], v[18:19], v[14:15] op_sel_hi:[0,1,1]
	v_lshlrev_b32_e32 v18, 16, v72
	v_and_b32_e32 v19, 0xffff0000, v72
	v_lshlrev_b32_e32 v20, 16, v73
	v_and_b32_e32 v21, 0xffff0000, v73
	v_pk_fma_f32 v[20:21], v[92:93], v[20:21], v[12:13] op_sel_hi:[0,1,1]
	v_pk_fma_f32 v[12:13], v[92:93], v[18:19], v[10:11] op_sel_hi:[0,1,1]
	v_mul_f32_e32 v10, v15, v15
	v_mul_f32_e32 v11, v17, v17
	v_fmac_f32_e32 v10, v14, v14
	v_fmac_f32_e32 v11, v16, v16
	v_add_f32_e32 v10, v10, v11
	v_mul_f32_e32 v11, v13, v13
	v_mul_f32_e32 v18, v21, v21
	v_fmac_f32_e32 v11, v12, v12
	v_fmac_f32_e32 v18, v20, v20
	v_add_f32_e32 v11, v11, v18
	v_add_f32_e32 v22, v10, v11
	v_lshl_add_u64 v[10:11], s[12:13], 0, v[94:95]
	v_lshl_add_u64 v[18:19], v[154:155], 1, v[10:11]
	v_cvt_pk_bf16_f32 v10, v14, v15
	v_cvt_pk_bf16_f32 v11, v16, v17
	v_cvt_pk_bf16_f32 v12, v12, v13
	v_cvt_pk_bf16_f32 v13, v20, v21
	global_store_dwordx4 v[18:19], v[10:13], off sc1
	s_nop 1
	v_lshlrev_b32_e32 v10, 16, v66
	v_and_b32_e32 v11, 0xffff0000, v66
	v_lshlrev_b32_e32 v12, 16, v67
	v_and_b32_e32 v13, 0xffff0000, v67
	v_pk_fma_f32 v[8:9], v[92:93], v[12:13], v[8:9] op_sel_hi:[0,1,1]
	v_pk_fma_f32 v[6:7], v[92:93], v[10:11], v[6:7] op_sel_hi:[0,1,1]
	v_lshlrev_b32_e32 v12, 16, v69
	v_and_b32_e32 v13, 0xffff0000, v69
	v_lshlrev_b32_e32 v10, 16, v68
	v_and_b32_e32 v11, 0xffff0000, v68
	v_pk_fma_f32 v[12:13], v[92:93], v[12:13], v[4:5] op_sel_hi:[0,1,1]
	v_mul_f32_e32 v4, v7, v7
	v_mul_f32_e32 v5, v9, v9
	v_pk_fma_f32 v[2:3], v[92:93], v[10:11], v[2:3] op_sel_hi:[0,1,1]
	v_fmac_f32_e32 v4, v6, v6
	v_fmac_f32_e32 v5, v8, v8
	v_add_f32_e32 v4, v4, v5
	v_mul_f32_e32 v5, v3, v3
	v_mul_f32_e32 v10, v13, v13
	v_fmac_f32_e32 v5, v2, v2
	v_fmac_f32_e32 v10, v12, v12
	v_add_f32_e32 v5, v5, v10
	v_add_f32_e32 v4, v4, v5
	v_add_f32_e32 v14, v22, v4
	ds_bpermute_b32 v15, v114, v14
	v_cvt_pk_bf16_f32 v4, v6, v7
	v_cvt_pk_bf16_f32 v6, v2, v3
	v_lshl_add_u64 v[10:11], v[18:19], 0, s[8:9]
	v_cvt_pk_bf16_f32 v5, v8, v9
	s_waitcnt lgkmcnt(0)
	v_add_f32_e32 v2, v14, v15
	ds_bpermute_b32 v3, v115, v2
	v_cvt_pk_bf16_f32 v7, v12, v13
	global_store_dwordx4 v[10:11], v[4:7], off sc1
	s_nop 1
	s_and_saveexec_b64 s[8:9], vcc
	s_cbranch_execz .LBB0_786
	v_lshl_add_u64 v[4:5], v[90:91], 2, s[10:11]
	s_waitcnt lgkmcnt(0)
	v_add_f32_e32 v2, v2, v3
	global_atomic_add_f32 v[4:5], v2, off
